# norm phases: mid-row s_waitcnt moved below the second batch of loads (one memory round trip per row), on top of peel+trims
# speedup vs baseline: 1.0055x; 1.0055x over previous
.LBB0_461:
	s_add_i32 s5, s4, 0xffffe000
	s_ashr_i32 s5, s5, 10
	s_add_i32 s5, s5, 1
	s_cmpk_gt_i32 s4, 0x1fff
	v_lshl_add_u64 v[34:35], s[6:7], 0, v[102:103]
	s_cselect_b32 s5, s5, 0
	v_add_co_u32_e32 v34, vcc, 0x27a00000, v34
	v_mad_i64_i32 v[36:37], s[8:9], s5, v245, v[98:99]
	s_nop 0
	v_addc_co_u32_e32 v35, vcc, 0, v35, vcc
	v_add_co_u32_e32 v70, vcc, 0x2000, v36
	s_nop 1
	v_addc_co_u32_e32 v71, vcc, 0, v37, vcc
	global_load_dwordx4 v[90:93], v[36:37], off
	global_load_dwordx4 v[82:85], v[36:37], off offset:1024
	global_load_dwordx4 v[94:97], v[70:71], off
	global_load_dwordx4 v[86:89], v[70:71], off offset:1024
	global_load_dwordx2 v[114:115], v[34:35], off
	global_load_dwordx2 v[116:117], v[34:35], off offset:512
	global_load_dwordx2 v[120:121], v[34:35], off offset:1024
	global_load_dwordx2 v[104:105], v[34:35], off offset:1536
	global_load_dwordx4 v[74:77], v[36:37], off offset:2048
	global_load_dwordx4 v[66:69], v[36:37], off offset:3072
	v_add_co_u32_e32 v38, vcc, s97, v36
	s_nop 1
	v_addc_co_u32_e32 v39, vcc, 0, v37, vcc
	v_add_co_u32_e32 v40, vcc, s91, v36
	s_nop 1
	v_addc_co_u32_e32 v41, vcc, 0, v37, vcc
	global_load_dwordx4 v[58:61], v[38:39], off
	global_load_dwordx4 v[50:53], v[38:39], off offset:1024
	global_load_dwordx4 v[62:65], v[40:41], off
	global_load_dwordx4 v[54:57], v[40:41], off offset:1024
	global_load_dwordx2 v[122:123], v[34:35], off offset:2048
	global_load_dwordx2 v[146:147], v[34:35], off offset:2560
	global_load_dwordx2 v[148:149], v[34:35], off offset:3072
	global_load_dwordx2 v[108:109], v[34:35], off offset:3584
	global_load_dwordx4 v[42:45], v[38:39], off offset:2048
	s_nop 0
	global_load_dwordx4 v[34:37], v[38:39], off offset:3072
	global_load_dwordx4 v[46:49], v[40:41], off offset:2048
	s_nop 0
	global_load_dwordx4 v[38:41], v[40:41], off offset:3072
	s_nop 0
	global_load_dwordx4 v[78:81], v[70:71], off offset:2048
	s_nop 0
	global_load_dwordx4 v[70:73], v[70:71], off offset:3072
	s_waitcnt vmcnt(14)
	v_lshlrev_b32_e32 v113, 16, v104
	v_and_b32_e32 v111, 0xffff0000, v104
	v_lshlrev_b32_e32 v118, 16, v105
	v_and_b32_e32 v119, 0xffff0000, v105
	s_waitcnt vmcnt(6)
	v_lshlrev_b32_e32 v107, 16, v108
	v_and_b32_e32 v105, 0xffff0000, v108
	v_lshlrev_b32_e32 v108, 16, v109
	v_and_b32_e32 v109, 0xffff0000, v109
	v_and_b32_e32 v139, 0xffff0000, v115
	v_and_b32_e32 v137, 0xffff0000, v114
	v_lshlrev_b32_e32 v138, 16, v115
	v_mul_f32_e32 v0, v139, v139
	v_lshlrev_b32_e32 v136, 16, v114
	v_pk_fma_f32 v[114:115], v[138:139], v[138:139], v[0:1] op_sel_hi:[1,1,0]
	v_and_b32_e32 v135, 0xffff0000, v117
	v_and_b32_e32 v134, 0xffff0000, v116
	v_mul_f32_e32 v0, v137, v137
	v_lshlrev_b32_e32 v133, 16, v117
	v_lshlrev_b32_e32 v132, 16, v116
	v_pk_mul_f32 v[116:117], v[134:135], v[134:135]
	v_lshlrev_b32_e32 v128, 16, v120
	v_and_b32_e32 v129, 0xffff0000, v120
	v_lshlrev_b32_e32 v130, 16, v121
	v_and_b32_e32 v131, 0xffff0000, v121
	v_pk_fma_f32 v[120:121], v[136:137], v[136:137], v[0:1] op_sel_hi:[1,1,0]
	v_pk_fma_f32 v[116:117], v[132:133], v[132:133], v[116:117]
	v_mov_b32_e32 v112, v120
	v_mov_b32_e32 v124, v114
	v_mov_b32_e32 v125, v113
	v_mul_f32_e32 v104, v111, v111
	v_pk_add_f32 v[114:115], v[120:121], v[114:115]
	v_pk_mul_f32 v[120:121], v[112:113], v[124:125]
	v_pk_add_f32 v[116:117], v[116:117], v[116:117] op_sel:[0,1] op_sel_hi:[1,0]
	v_mov_b32_e32 v115, v121
	v_mov_b32_e32 v117, v104
	v_mul_f32_e32 v0, v129, v129
	v_pk_add_f32 v[114:115], v[114:115], v[116:117]
	v_pk_fma_f32 v[116:117], v[128:129], v[128:129], v[0:1] op_sel_hi:[1,1,0]
	v_mul_f32_e32 v0, v131, v131
	v_mul_f32_e32 v106, v118, v118
	v_mul_f32_e32 v110, v119, v119
	v_pk_fma_f32 v[120:121], v[130:131], v[130:131], v[0:1] op_sel_hi:[1,1,0]
	v_mov_b32_e32 v117, v106
	v_mov_b32_e32 v121, v110
	v_pk_add_f32 v[116:117], v[116:117], v[120:121]
	v_and_b32_e32 v127, 0xffff0000, v123
	v_and_b32_e32 v126, 0xffff0000, v122
	v_pk_add_f32 v[150:151], v[114:115], v[116:117]
	v_lshlrev_b32_e32 v125, 16, v123
	v_lshlrev_b32_e32 v124, 16, v122
	v_pk_mul_f32 v[114:115], v[126:127], v[126:127]
	v_and_b32_e32 v123, 0xffff0000, v147
	v_pk_fma_f32 v[114:115], v[124:125], v[124:125], v[114:115]
	v_and_b32_e32 v122, 0xffff0000, v146
	v_pk_add_f32 v[152:153], v[114:115], v[114:115] op_sel:[0,1] op_sel_hi:[1,0]
	v_lshlrev_b32_e32 v121, 16, v147
	v_lshlrev_b32_e32 v120, 16, v146
	v_pk_mul_f32 v[114:115], v[122:123], v[122:123]
	v_lshlrev_b32_e32 v116, 16, v149
	v_pk_fma_f32 v[146:147], v[120:121], v[120:121], v[114:115]
	v_lshlrev_b32_e32 v114, 16, v148
	v_and_b32_e32 v115, 0xffff0000, v148
	v_and_b32_e32 v117, 0xffff0000, v149
	v_pk_add_f32 v[148:149], v[150:151], v[150:151] op_sel:[0,1] op_sel_hi:[1,0]
	v_mov_b32_e32 v150, v152
	v_mov_b32_e32 v106, v148
	v_mov_b32_e32 v151, v107
	v_mul_f32_e32 v0, v105, v105
	v_pk_add_f32 v[148:149], v[148:149], v[152:153]
	v_pk_mul_f32 v[150:151], v[106:107], v[150:151]
	v_pk_add_f32 v[146:147], v[146:147], v[146:147] op_sel:[0,1] op_sel_hi:[1,0]
	v_mov_b32_e32 v149, v151
	v_mov_b32_e32 v147, v0
	v_mul_f32_e32 v0, v115, v115
	v_pk_add_f32 v[146:147], v[148:149], v[146:147]
	v_pk_fma_f32 v[148:149], v[114:115], v[114:115], v[0:1] op_sel_hi:[1,1,0]
	v_mul_f32_e32 v0, v117, v117
	v_mul_f32_e32 v104, v108, v108
	v_mul_f32_e32 v110, v109, v109
	v_pk_fma_f32 v[150:151], v[116:117], v[116:117], v[0:1] op_sel_hi:[1,1,0]
	v_mov_b32_e32 v149, v104
	v_mov_b32_e32 v151, v110
	v_pk_add_f32 v[148:149], v[148:149], v[150:151]
	v_pk_add_f32 v[94:95], v[94:95], 1.0 op_sel_hi:[1,0]
	v_pk_add_f32 v[146:147], v[146:147], v[148:149]
	v_pk_add_f32 v[96:97], v[96:97], 1.0 op_sel_hi:[1,0]
	v_add_f32_e32 v0, v146, v147
	ds_bpermute_b32 v104, v140, v0
	v_lshl_add_u64 v[146:147], s[6:7], 0, v[100:101]
	v_pk_add_f32 v[88:89], v[88:89], 1.0 op_sel_hi:[1,0]
	v_pk_add_f32 v[86:87], v[86:87], 1.0 op_sel_hi:[1,0]
	s_waitcnt vmcnt(1)
	v_pk_add_f32 v[80:81], v[80:81], 1.0 op_sel_hi:[1,0]
	s_waitcnt lgkmcnt(0)
	v_add_f32_e32 v0, v0, v104
	ds_bpermute_b32 v104, v141, v0
	v_pk_add_f32 v[78:79], v[78:79], 1.0 op_sel_hi:[1,0]
	v_mov_b32_e32 v110, v113
	s_waitcnt vmcnt(0)
	v_pk_add_f32 v[72:73], v[72:73], 1.0 op_sel_hi:[1,0]
	v_pk_add_f32 v[70:71], v[70:71], 1.0 op_sel_hi:[1,0]
	s_waitcnt lgkmcnt(0)
	v_add_f32_e32 v0, v0, v104
	ds_bpermute_b32 v104, v142, v0
	v_pk_add_f32 v[64:65], v[64:65], 1.0 op_sel_hi:[1,0]
	v_pk_add_f32 v[62:63], v[62:63], 1.0 op_sel_hi:[1,0]
	v_pk_add_f32 v[56:57], v[56:57], 1.0 op_sel_hi:[1,0]
	v_pk_add_f32 v[54:55], v[54:55], 1.0 op_sel_hi:[1,0]
	s_waitcnt lgkmcnt(0)
	v_add_f32_e32 v0, v0, v104
	ds_bpermute_b32 v104, v143, v0
	v_pk_add_f32 v[48:49], v[48:49], 1.0 op_sel_hi:[1,0]
	v_pk_add_f32 v[46:47], v[46:47], 1.0 op_sel_hi:[1,0]
	v_readlane_b32 s8, v254, 13
	s_add_i32 s4, s4, s8
	s_waitcnt lgkmcnt(0)
	v_add_f32_e32 v0, v0, v104
	ds_bpermute_b32 v104, v144, v0
	v_pk_add_f32 v[40:41], v[40:41], 1.0 op_sel_hi:[1,0]
	v_pk_add_f32 v[38:39], v[38:39], 1.0 op_sel_hi:[1,0]
	s_add_u32 s6, s6, s86
	s_addc_u32 s7, s7, s87
	s_waitcnt lgkmcnt(0)
	v_add_f32_e32 v0, v0, v104
	ds_bpermute_b32 v104, v145, v0
	s_cmpk_lt_i32 s4, 0x2800
	v_readlane_b32 s9, v254, 14
	s_waitcnt lgkmcnt(0)
	v_add_f32_e32 v0, v0, v104
	v_fmamk_f32 v0, v0, 0x3a000000, v224
	v_rsq_f32_e32 v0, v0
	v_mov_b32_e32 v104, v107
	v_pk_mul_f32 v[136:137], v[0:1], v[136:137] op_sel_hi:[0,1]
	v_pk_mul_f32 v[138:139], v[0:1], v[138:139] op_sel_hi:[0,1]
	v_pk_mul_f32 v[136:137], v[2:3], v[136:137]
	v_pk_mul_f32 v[138:139], v[4:5], v[138:139]
	v_pk_fma_f32 v[90:91], v[94:95], v[136:137], v[90:91]
	v_pk_fma_f32 v[92:93], v[96:97], v[138:139], v[92:93]
	v_cvt_pk_bf16_f32 v94, v90, v91
	v_add_co_u32_e32 v90, vcc, s51, v146
	v_cvt_pk_bf16_f32 v95, v92, v93
	s_nop 0
	v_addc_co_u32_e32 v91, vcc, 0, v147, vcc
	v_mov_b32_e32 v92, v133
	v_mov_b32_e32 v93, v135
	v_mov_b32_e32 v133, v134
	global_store_dwordx2 v[90:91], v[94:95], off
	v_pk_mul_f32 v[92:93], v[0:1], v[92:93] op_sel_hi:[0,1]
	v_pk_mul_f32 v[94:95], v[0:1], v[132:133] op_sel_hi:[0,1]
	v_pk_mul_f32 v[94:95], v[6:7], v[94:95]
	v_pk_mul_f32 v[92:93], v[8:9], v[92:93]
	v_pk_fma_f32 v[82:83], v[86:87], v[94:95], v[82:83]
	v_pk_fma_f32 v[84:85], v[88:89], v[92:93], v[84:85]
	v_cvt_pk_bf16_f32 v82, v82, v83
	v_cvt_pk_bf16_f32 v83, v84, v85
	global_store_dwordx2 v[90:91], v[82:83], off offset:512
	v_pk_mul_f32 v[82:83], v[0:1], v[130:131] op_sel_hi:[0,1]
	v_pk_mul_f32 v[84:85], v[0:1], v[128:129] op_sel_hi:[0,1]
	v_pk_mul_f32 v[84:85], v[10:11], v[84:85]
	v_pk_mul_f32 v[82:83], v[12:13], v[82:83]
	v_pk_fma_f32 v[74:75], v[78:79], v[84:85], v[74:75]
	v_pk_fma_f32 v[76:77], v[80:81], v[82:83], v[76:77]
	v_cvt_pk_bf16_f32 v74, v74, v75
	v_cvt_pk_bf16_f32 v75, v76, v77
	global_store_dwordx2 v[90:91], v[74:75], off offset:1024
	v_pk_mul_f32 v[74:75], v[118:119], v[0:1] op_sel_hi:[1,0]
	v_pk_mul_f32 v[76:77], v[110:111], v[0:1] op_sel_hi:[1,0]
	v_pk_mul_f32 v[74:75], v[16:17], v[74:75]
	v_pk_mul_f32 v[76:77], v[14:15], v[76:77]
	v_pk_fma_f32 v[68:69], v[72:73], v[74:75], v[68:69]
	v_pk_fma_f32 v[66:67], v[70:71], v[76:77], v[66:67]
	s_nop 0
	v_cvt_pk_bf16_f32 v66, v66, v67
	v_cvt_pk_bf16_f32 v67, v68, v69
	global_store_dwordx2 v[90:91], v[66:67], off offset:1536
	v_mov_b32_e32 v66, v125
	v_mov_b32_e32 v67, v127
	v_mov_b32_e32 v125, v126
	v_pk_mul_f32 v[66:67], v[0:1], v[66:67] op_sel_hi:[0,1]
	v_pk_mul_f32 v[68:69], v[0:1], v[124:125] op_sel_hi:[0,1]
	v_pk_mul_f32 v[68:69], v[18:19], v[68:69]
	v_pk_mul_f32 v[66:67], v[20:21], v[66:67]
	v_pk_fma_f32 v[58:59], v[62:63], v[68:69], v[58:59]
	v_pk_fma_f32 v[60:61], v[64:65], v[66:67], v[60:61]
	v_cvt_pk_bf16_f32 v58, v58, v59
	v_cvt_pk_bf16_f32 v59, v60, v61
	global_store_dwordx2 v[90:91], v[58:59], off offset:2048
	v_mov_b32_e32 v58, v121
	v_mov_b32_e32 v59, v123
	v_mov_b32_e32 v121, v122
	v_pk_mul_f32 v[58:59], v[0:1], v[58:59] op_sel_hi:[0,1]
	v_pk_mul_f32 v[60:61], v[0:1], v[120:121] op_sel_hi:[0,1]
	v_pk_mul_f32 v[60:61], v[22:23], v[60:61]
	v_pk_mul_f32 v[58:59], v[24:25], v[58:59]
	v_pk_fma_f32 v[50:51], v[54:55], v[60:61], v[50:51]
	v_pk_fma_f32 v[52:53], v[56:57], v[58:59], v[52:53]
	v_cvt_pk_bf16_f32 v50, v50, v51
	v_cvt_pk_bf16_f32 v51, v52, v53
	global_store_dwordx2 v[90:91], v[50:51], off offset:2560
	v_pk_mul_f32 v[50:51], v[0:1], v[116:117] op_sel_hi:[0,1]
	v_pk_mul_f32 v[52:53], v[0:1], v[114:115] op_sel_hi:[0,1]
	v_pk_mul_f32 v[52:53], v[26:27], v[52:53]
	v_pk_mul_f32 v[50:51], v[28:29], v[50:51]
	v_pk_fma_f32 v[42:43], v[46:47], v[52:53], v[42:43]
	v_pk_fma_f32 v[44:45], v[48:49], v[50:51], v[44:45]
	v_cvt_pk_bf16_f32 v42, v42, v43
	v_cvt_pk_bf16_f32 v43, v44, v45
	global_store_dwordx2 v[90:91], v[42:43], off offset:3072
	v_pk_mul_f32 v[42:43], v[108:109], v[0:1] op_sel_hi:[1,0]
	v_pk_mul_f32 v[44:45], v[104:105], v[0:1] op_sel_hi:[1,0]
	v_pk_mul_f32 v[42:43], v[32:33], v[42:43]
	v_pk_mul_f32 v[44:45], v[30:31], v[44:45]
	v_pk_fma_f32 v[36:37], v[40:41], v[42:43], v[36:37]
	v_pk_fma_f32 v[34:35], v[38:39], v[44:45], v[34:35]
	s_nop 0
	v_cvt_pk_bf16_f32 v34, v34, v35
	v_cvt_pk_bf16_f32 v35, v36, v37
	global_store_dwordx2 v[90:91], v[34:35], off offset:3584
	s_cbranch_scc1 .LBB0_461

.LBB0_992:
	s_add_i32 s4, s8, 0xffffe000
	s_ashr_i32 s4, s4, 10
	s_add_i32 s4, s4, 1
	s_cmpk_gt_i32 s8, 0x1fff
	v_lshl_add_u64 v[34:35], s[10:11], 0, v[102:103]
	s_cselect_b32 s4, s4, 0
	v_add_co_u32_e32 v34, vcc, 0x27a00000, v34
	v_mad_i64_i32 v[36:37], s[4:5], s4, v245, v[98:99]
	s_nop 0
	v_addc_co_u32_e32 v35, vcc, 0, v35, vcc
	v_add_co_u32_e32 v70, vcc, 0x2000, v36
	s_nop 1
	v_addc_co_u32_e32 v71, vcc, 0, v37, vcc
	global_load_dwordx4 v[90:93], v[36:37], off
	global_load_dwordx4 v[82:85], v[36:37], off offset:1024
	global_load_dwordx4 v[94:97], v[70:71], off
	global_load_dwordx4 v[86:89], v[70:71], off offset:1024
	global_load_dwordx2 v[114:115], v[34:35], off
	global_load_dwordx2 v[116:117], v[34:35], off offset:512
	global_load_dwordx2 v[120:121], v[34:35], off offset:1024
	global_load_dwordx2 v[104:105], v[34:35], off offset:1536
	global_load_dwordx4 v[74:77], v[36:37], off offset:2048
	global_load_dwordx4 v[66:69], v[36:37], off offset:3072
	v_add_co_u32_e32 v38, vcc, s97, v36
	s_nop 1
	v_addc_co_u32_e32 v39, vcc, 0, v37, vcc
	v_add_co_u32_e32 v40, vcc, s91, v36
	s_nop 1
	v_addc_co_u32_e32 v41, vcc, 0, v37, vcc
	global_load_dwordx4 v[58:61], v[38:39], off
	global_load_dwordx4 v[50:53], v[38:39], off offset:1024
	global_load_dwordx4 v[62:65], v[40:41], off
	global_load_dwordx4 v[54:57], v[40:41], off offset:1024
	global_load_dwordx2 v[122:123], v[34:35], off offset:2048
	global_load_dwordx2 v[146:147], v[34:35], off offset:2560
	global_load_dwordx2 v[148:149], v[34:35], off offset:3072
	global_load_dwordx2 v[108:109], v[34:35], off offset:3584
	global_load_dwordx4 v[42:45], v[38:39], off offset:2048
	s_nop 0
	global_load_dwordx4 v[34:37], v[38:39], off offset:3072
	global_load_dwordx4 v[46:49], v[40:41], off offset:2048
	s_nop 0
	global_load_dwordx4 v[38:41], v[40:41], off offset:3072
	s_nop 0
	global_load_dwordx4 v[78:81], v[70:71], off offset:2048
	s_nop 0
	global_load_dwordx4 v[70:73], v[70:71], off offset:3072
	s_waitcnt vmcnt(14)
	v_lshlrev_b32_e32 v113, 16, v104
	v_and_b32_e32 v111, 0xffff0000, v104
	v_lshlrev_b32_e32 v118, 16, v105
	v_and_b32_e32 v119, 0xffff0000, v105
	s_waitcnt vmcnt(6)
	v_lshlrev_b32_e32 v107, 16, v108
	v_and_b32_e32 v105, 0xffff0000, v108
	v_lshlrev_b32_e32 v108, 16, v109
	v_and_b32_e32 v109, 0xffff0000, v109
	v_and_b32_e32 v139, 0xffff0000, v115
	v_and_b32_e32 v137, 0xffff0000, v114
	v_lshlrev_b32_e32 v138, 16, v115
	v_mul_f32_e32 v0, v139, v139
	v_lshlrev_b32_e32 v136, 16, v114
	v_pk_fma_f32 v[114:115], v[138:139], v[138:139], v[0:1] op_sel_hi:[1,1,0]
	v_and_b32_e32 v135, 0xffff0000, v117
	v_and_b32_e32 v134, 0xffff0000, v116
	v_mul_f32_e32 v0, v137, v137
	v_lshlrev_b32_e32 v133, 16, v117
	v_lshlrev_b32_e32 v132, 16, v116
	v_pk_mul_f32 v[116:117], v[134:135], v[134:135]
	v_lshlrev_b32_e32 v128, 16, v120
	v_and_b32_e32 v129, 0xffff0000, v120
	v_lshlrev_b32_e32 v130, 16, v121
	v_and_b32_e32 v131, 0xffff0000, v121
	v_pk_fma_f32 v[120:121], v[136:137], v[136:137], v[0:1] op_sel_hi:[1,1,0]
	v_pk_fma_f32 v[116:117], v[132:133], v[132:133], v[116:117]
	v_mov_b32_e32 v112, v120
	v_mov_b32_e32 v124, v114
	v_mov_b32_e32 v125, v113
	v_mul_f32_e32 v104, v111, v111
	v_pk_add_f32 v[114:115], v[120:121], v[114:115]
	v_pk_mul_f32 v[120:121], v[112:113], v[124:125]
	v_pk_add_f32 v[116:117], v[116:117], v[116:117] op_sel:[0,1] op_sel_hi:[1,0]
	v_mov_b32_e32 v115, v121
	v_mov_b32_e32 v117, v104
	v_mul_f32_e32 v0, v129, v129
	v_pk_add_f32 v[114:115], v[114:115], v[116:117]
	v_pk_fma_f32 v[116:117], v[128:129], v[128:129], v[0:1] op_sel_hi:[1,1,0]
	v_mul_f32_e32 v0, v131, v131
	v_mul_f32_e32 v106, v118, v118
	v_mul_f32_e32 v110, v119, v119
	v_pk_fma_f32 v[120:121], v[130:131], v[130:131], v[0:1] op_sel_hi:[1,1,0]
	v_mov_b32_e32 v117, v106
	v_mov_b32_e32 v121, v110
	v_pk_add_f32 v[116:117], v[116:117], v[120:121]
	v_and_b32_e32 v127, 0xffff0000, v123
	v_and_b32_e32 v126, 0xffff0000, v122
	v_pk_add_f32 v[150:151], v[114:115], v[116:117]
	v_lshlrev_b32_e32 v125, 16, v123
	v_lshlrev_b32_e32 v124, 16, v122
	v_pk_mul_f32 v[114:115], v[126:127], v[126:127]
	v_and_b32_e32 v123, 0xffff0000, v147
	v_pk_fma_f32 v[114:115], v[124:125], v[124:125], v[114:115]
	v_and_b32_e32 v122, 0xffff0000, v146
	v_pk_add_f32 v[152:153], v[114:115], v[114:115] op_sel:[0,1] op_sel_hi:[1,0]
	v_lshlrev_b32_e32 v121, 16, v147
	v_lshlrev_b32_e32 v120, 16, v146
	v_pk_mul_f32 v[114:115], v[122:123], v[122:123]
	v_lshlrev_b32_e32 v116, 16, v149
	v_pk_fma_f32 v[146:147], v[120:121], v[120:121], v[114:115]
	v_lshlrev_b32_e32 v114, 16, v148
	v_and_b32_e32 v115, 0xffff0000, v148
	v_and_b32_e32 v117, 0xffff0000, v149
	v_pk_add_f32 v[148:149], v[150:151], v[150:151] op_sel:[0,1] op_sel_hi:[1,0]
	v_mov_b32_e32 v150, v152
	v_mov_b32_e32 v106, v148
	v_mov_b32_e32 v151, v107
	v_mul_f32_e32 v0, v105, v105
	v_pk_add_f32 v[148:149], v[148:149], v[152:153]
	v_pk_mul_f32 v[150:151], v[106:107], v[150:151]
	v_pk_add_f32 v[146:147], v[146:147], v[146:147] op_sel:[0,1] op_sel_hi:[1,0]
	v_mov_b32_e32 v149, v151
	v_mov_b32_e32 v147, v0
	v_mul_f32_e32 v0, v115, v115
	v_pk_add_f32 v[146:147], v[148:149], v[146:147]
	v_pk_fma_f32 v[148:149], v[114:115], v[114:115], v[0:1] op_sel_hi:[1,1,0]
	v_mul_f32_e32 v0, v117, v117
	v_mul_f32_e32 v104, v108, v108
	v_mul_f32_e32 v110, v109, v109
	v_pk_fma_f32 v[150:151], v[116:117], v[116:117], v[0:1] op_sel_hi:[1,1,0]
	v_mov_b32_e32 v149, v104
	v_mov_b32_e32 v151, v110
	v_pk_add_f32 v[148:149], v[148:149], v[150:151]
	v_pk_add_f32 v[94:95], v[94:95], 1.0 op_sel_hi:[1,0]
	v_pk_add_f32 v[146:147], v[146:147], v[148:149]
	v_pk_add_f32 v[96:97], v[96:97], 1.0 op_sel_hi:[1,0]
	v_add_f32_e32 v0, v146, v147
	ds_bpermute_b32 v104, v140, v0
	v_lshl_add_u64 v[146:147], s[10:11], 0, v[100:101]
	v_pk_add_f32 v[88:89], v[88:89], 1.0 op_sel_hi:[1,0]
	v_pk_add_f32 v[86:87], v[86:87], 1.0 op_sel_hi:[1,0]
	s_waitcnt vmcnt(1)
	v_pk_add_f32 v[80:81], v[80:81], 1.0 op_sel_hi:[1,0]
	s_waitcnt lgkmcnt(0)
	v_add_f32_e32 v0, v0, v104
	ds_bpermute_b32 v104, v141, v0
	v_pk_add_f32 v[78:79], v[78:79], 1.0 op_sel_hi:[1,0]
	v_mov_b32_e32 v110, v113
	s_waitcnt vmcnt(0)
	v_pk_add_f32 v[72:73], v[72:73], 1.0 op_sel_hi:[1,0]
	v_pk_add_f32 v[70:71], v[70:71], 1.0 op_sel_hi:[1,0]
	s_waitcnt lgkmcnt(0)
	v_add_f32_e32 v0, v0, v104
	ds_bpermute_b32 v104, v142, v0
	v_pk_add_f32 v[64:65], v[64:65], 1.0 op_sel_hi:[1,0]
	v_pk_add_f32 v[62:63], v[62:63], 1.0 op_sel_hi:[1,0]
	v_pk_add_f32 v[56:57], v[56:57], 1.0 op_sel_hi:[1,0]
	v_pk_add_f32 v[54:55], v[54:55], 1.0 op_sel_hi:[1,0]
	s_waitcnt lgkmcnt(0)
	v_add_f32_e32 v0, v0, v104
	ds_bpermute_b32 v104, v143, v0
	v_pk_add_f32 v[48:49], v[48:49], 1.0 op_sel_hi:[1,0]
	v_pk_add_f32 v[46:47], v[46:47], 1.0 op_sel_hi:[1,0]
	v_readlane_b32 s4, v254, 13
	s_add_i32 s8, s8, s4
	s_waitcnt lgkmcnt(0)
	v_add_f32_e32 v0, v0, v104
	ds_bpermute_b32 v104, v144, v0
	v_pk_add_f32 v[40:41], v[40:41], 1.0 op_sel_hi:[1,0]
	v_pk_add_f32 v[38:39], v[38:39], 1.0 op_sel_hi:[1,0]
	s_add_u32 s10, s10, s86
	s_addc_u32 s11, s11, s87
	s_waitcnt lgkmcnt(0)
	v_add_f32_e32 v0, v0, v104
	ds_bpermute_b32 v104, v145, v0
	s_cmpk_lt_i32 s8, 0x2800
	v_readlane_b32 s5, v254, 14
	s_waitcnt lgkmcnt(0)
	v_add_f32_e32 v0, v0, v104
	v_fmamk_f32 v0, v0, 0x3a000000, v224
	v_rsq_f32_e32 v0, v0
	v_mov_b32_e32 v104, v107
	v_pk_mul_f32 v[136:137], v[0:1], v[136:137] op_sel_hi:[0,1]
	v_pk_mul_f32 v[138:139], v[0:1], v[138:139] op_sel_hi:[0,1]
	v_pk_mul_f32 v[136:137], v[10:11], v[136:137]
	v_pk_mul_f32 v[138:139], v[12:13], v[138:139]
	v_pk_fma_f32 v[90:91], v[94:95], v[136:137], v[90:91]
	v_pk_fma_f32 v[92:93], v[96:97], v[138:139], v[92:93]
	v_cvt_pk_bf16_f32 v94, v90, v91
	v_add_co_u32_e32 v90, vcc, s51, v146
	v_cvt_pk_bf16_f32 v95, v92, v93
	s_nop 0
	v_addc_co_u32_e32 v91, vcc, 0, v147, vcc
	v_mov_b32_e32 v92, v133
	v_mov_b32_e32 v93, v135
	v_mov_b32_e32 v133, v134
	global_store_dwordx2 v[90:91], v[94:95], off
	v_pk_mul_f32 v[92:93], v[0:1], v[92:93] op_sel_hi:[0,1]
	v_pk_mul_f32 v[94:95], v[0:1], v[132:133] op_sel_hi:[0,1]
	v_pk_mul_f32 v[94:95], v[2:3], v[94:95]
	v_pk_mul_f32 v[92:93], v[4:5], v[92:93]
	v_pk_fma_f32 v[82:83], v[86:87], v[94:95], v[82:83]
	v_pk_fma_f32 v[84:85], v[88:89], v[92:93], v[84:85]
	v_cvt_pk_bf16_f32 v82, v82, v83
	v_cvt_pk_bf16_f32 v83, v84, v85
	global_store_dwordx2 v[90:91], v[82:83], off offset:512
	v_pk_mul_f32 v[82:83], v[0:1], v[130:131] op_sel_hi:[0,1]
	v_pk_mul_f32 v[84:85], v[0:1], v[128:129] op_sel_hi:[0,1]
	v_pk_mul_f32 v[84:85], v[6:7], v[84:85]
	v_pk_mul_f32 v[82:83], v[8:9], v[82:83]
	v_pk_fma_f32 v[74:75], v[78:79], v[84:85], v[74:75]
	v_pk_fma_f32 v[76:77], v[80:81], v[82:83], v[76:77]
	v_cvt_pk_bf16_f32 v74, v74, v75
	v_cvt_pk_bf16_f32 v75, v76, v77
	global_store_dwordx2 v[90:91], v[74:75], off offset:1024
	v_pk_mul_f32 v[74:75], v[118:119], v[0:1] op_sel_hi:[1,0]
	v_pk_mul_f32 v[76:77], v[110:111], v[0:1] op_sel_hi:[1,0]
	v_pk_mul_f32 v[74:75], v[16:17], v[74:75]
	v_pk_mul_f32 v[76:77], v[14:15], v[76:77]
	v_pk_fma_f32 v[68:69], v[72:73], v[74:75], v[68:69]
	v_pk_fma_f32 v[66:67], v[70:71], v[76:77], v[66:67]
	s_nop 0
	v_cvt_pk_bf16_f32 v66, v66, v67
	v_cvt_pk_bf16_f32 v67, v68, v69
	global_store_dwordx2 v[90:91], v[66:67], off offset:1536
	v_mov_b32_e32 v66, v125
	v_mov_b32_e32 v67, v127
	v_mov_b32_e32 v125, v126
	v_pk_mul_f32 v[66:67], v[0:1], v[66:67] op_sel_hi:[0,1]
	v_pk_mul_f32 v[68:69], v[0:1], v[124:125] op_sel_hi:[0,1]
	v_pk_mul_f32 v[68:69], v[18:19], v[68:69]
	v_pk_mul_f32 v[66:67], v[20:21], v[66:67]
	v_pk_fma_f32 v[58:59], v[62:63], v[68:69], v[58:59]
	v_pk_fma_f32 v[60:61], v[64:65], v[66:67], v[60:61]
	v_cvt_pk_bf16_f32 v58, v58, v59
	v_cvt_pk_bf16_f32 v59, v60, v61
	global_store_dwordx2 v[90:91], v[58:59], off offset:2048
	v_mov_b32_e32 v58, v121
	v_mov_b32_e32 v59, v123
	v_mov_b32_e32 v121, v122
	v_pk_mul_f32 v[58:59], v[0:1], v[58:59] op_sel_hi:[0,1]
	v_pk_mul_f32 v[60:61], v[0:1], v[120:121] op_sel_hi:[0,1]
	v_pk_mul_f32 v[60:61], v[22:23], v[60:61]
	v_pk_mul_f32 v[58:59], v[24:25], v[58:59]
	v_pk_fma_f32 v[50:51], v[54:55], v[60:61], v[50:51]
	v_pk_fma_f32 v[52:53], v[56:57], v[58:59], v[52:53]
	v_cvt_pk_bf16_f32 v50, v50, v51
	v_cvt_pk_bf16_f32 v51, v52, v53
	global_store_dwordx2 v[90:91], v[50:51], off offset:2560
	v_pk_mul_f32 v[50:51], v[0:1], v[116:117] op_sel_hi:[0,1]
	v_pk_mul_f32 v[52:53], v[0:1], v[114:115] op_sel_hi:[0,1]
	v_pk_mul_f32 v[52:53], v[26:27], v[52:53]
	v_pk_mul_f32 v[50:51], v[28:29], v[50:51]
	v_pk_fma_f32 v[42:43], v[46:47], v[52:53], v[42:43]
	v_pk_fma_f32 v[44:45], v[48:49], v[50:51], v[44:45]
	v_cvt_pk_bf16_f32 v42, v42, v43
	v_cvt_pk_bf16_f32 v43, v44, v45
	global_store_dwordx2 v[90:91], v[42:43], off offset:3072
	v_pk_mul_f32 v[42:43], v[108:109], v[0:1] op_sel_hi:[1,0]
	v_pk_mul_f32 v[44:45], v[104:105], v[0:1] op_sel_hi:[1,0]
	v_pk_mul_f32 v[42:43], v[32:33], v[42:43]
	v_pk_mul_f32 v[44:45], v[30:31], v[44:45]
	v_pk_fma_f32 v[36:37], v[40:41], v[42:43], v[36:37]
	v_pk_fma_f32 v[34:35], v[38:39], v[44:45], v[34:35]
	s_nop 0
	v_cvt_pk_bf16_f32 v34, v34, v35
	v_cvt_pk_bf16_f32 v35, v36, v37
	global_store_dwordx2 v[90:91], v[34:35], off offset:3584
	s_cbranch_scc1 .LBB0_992

.LBB0_1600:
	s_add_i32 s5, s4, 0xffffe000
	s_ashr_i32 s5, s5, 10
	s_add_i32 s5, s5, 1
	s_cmpk_gt_i32 s4, 0x1fff
	v_lshl_add_u64 v[34:35], s[8:9], 0, v[102:103]
	s_cselect_b32 s5, s5, 0
	v_add_co_u32_e32 v34, vcc, 0x27a00000, v34
	v_mad_i64_i32 v[36:37], s[6:7], s5, v245, v[98:99]
	s_nop 0
	v_addc_co_u32_e32 v35, vcc, 0, v35, vcc
	v_add_co_u32_e32 v70, vcc, 0x2000, v36
	s_nop 1
	v_addc_co_u32_e32 v71, vcc, 0, v37, vcc
	global_load_dwordx4 v[90:93], v[36:37], off
	global_load_dwordx4 v[82:85], v[36:37], off offset:1024
	global_load_dwordx4 v[94:97], v[70:71], off
	global_load_dwordx4 v[86:89], v[70:71], off offset:1024
	global_load_dwordx2 v[114:115], v[34:35], off
	global_load_dwordx2 v[116:117], v[34:35], off offset:512
	global_load_dwordx2 v[120:121], v[34:35], off offset:1024
	global_load_dwordx2 v[104:105], v[34:35], off offset:1536
	global_load_dwordx4 v[74:77], v[36:37], off offset:2048
	global_load_dwordx4 v[66:69], v[36:37], off offset:3072
	v_add_co_u32_e32 v38, vcc, s97, v36
	s_nop 1
	v_addc_co_u32_e32 v39, vcc, 0, v37, vcc
	v_add_co_u32_e32 v40, vcc, s91, v36
	s_nop 1
	v_addc_co_u32_e32 v41, vcc, 0, v37, vcc
	global_load_dwordx4 v[58:61], v[38:39], off
	global_load_dwordx4 v[50:53], v[38:39], off offset:1024
	global_load_dwordx4 v[62:65], v[40:41], off
	global_load_dwordx4 v[54:57], v[40:41], off offset:1024
	global_load_dwordx2 v[122:123], v[34:35], off offset:2048
	global_load_dwordx2 v[146:147], v[34:35], off offset:2560
	global_load_dwordx2 v[148:149], v[34:35], off offset:3072
	global_load_dwordx2 v[108:109], v[34:35], off offset:3584
	global_load_dwordx4 v[42:45], v[38:39], off offset:2048
	s_nop 0
	global_load_dwordx4 v[34:37], v[38:39], off offset:3072
	global_load_dwordx4 v[46:49], v[40:41], off offset:2048
	s_nop 0
	global_load_dwordx4 v[38:41], v[40:41], off offset:3072
	s_nop 0
	global_load_dwordx4 v[78:81], v[70:71], off offset:2048
	s_nop 0
	global_load_dwordx4 v[70:73], v[70:71], off offset:3072
	s_waitcnt vmcnt(14)
	v_lshlrev_b32_e32 v113, 16, v104
	v_and_b32_e32 v111, 0xffff0000, v104
	v_lshlrev_b32_e32 v118, 16, v105
	v_and_b32_e32 v119, 0xffff0000, v105
	s_waitcnt vmcnt(6)
	v_lshlrev_b32_e32 v107, 16, v108
	v_and_b32_e32 v105, 0xffff0000, v108
	v_lshlrev_b32_e32 v108, 16, v109
	v_and_b32_e32 v109, 0xffff0000, v109
	v_and_b32_e32 v139, 0xffff0000, v115
	v_and_b32_e32 v137, 0xffff0000, v114
	v_lshlrev_b32_e32 v138, 16, v115
	v_mul_f32_e32 v0, v139, v139
	v_lshlrev_b32_e32 v136, 16, v114
	v_pk_fma_f32 v[114:115], v[138:139], v[138:139], v[0:1] op_sel_hi:[1,1,0]
	v_and_b32_e32 v135, 0xffff0000, v117
	v_and_b32_e32 v134, 0xffff0000, v116
	v_mul_f32_e32 v0, v137, v137
	v_lshlrev_b32_e32 v133, 16, v117
	v_lshlrev_b32_e32 v132, 16, v116
	v_pk_mul_f32 v[116:117], v[134:135], v[134:135]
	v_lshlrev_b32_e32 v128, 16, v120
	v_and_b32_e32 v129, 0xffff0000, v120
	v_lshlrev_b32_e32 v130, 16, v121
	v_and_b32_e32 v131, 0xffff0000, v121
	v_pk_fma_f32 v[120:121], v[136:137], v[136:137], v[0:1] op_sel_hi:[1,1,0]
	v_pk_fma_f32 v[116:117], v[132:133], v[132:133], v[116:117]
	v_mov_b32_e32 v112, v120
	v_mov_b32_e32 v124, v114
	v_mov_b32_e32 v125, v113
	v_mul_f32_e32 v104, v111, v111
	v_pk_add_f32 v[114:115], v[120:121], v[114:115]
	v_pk_mul_f32 v[120:121], v[112:113], v[124:125]
	v_pk_add_f32 v[116:117], v[116:117], v[116:117] op_sel:[0,1] op_sel_hi:[1,0]
	v_mov_b32_e32 v115, v121
	v_mov_b32_e32 v117, v104
	v_mul_f32_e32 v0, v129, v129
	v_pk_add_f32 v[114:115], v[114:115], v[116:117]
	v_pk_fma_f32 v[116:117], v[128:129], v[128:129], v[0:1] op_sel_hi:[1,1,0]
	v_mul_f32_e32 v0, v131, v131
	v_mul_f32_e32 v106, v118, v118
	v_mul_f32_e32 v110, v119, v119
	v_pk_fma_f32 v[120:121], v[130:131], v[130:131], v[0:1] op_sel_hi:[1,1,0]
	v_mov_b32_e32 v117, v106
	v_mov_b32_e32 v121, v110
	v_pk_add_f32 v[116:117], v[116:117], v[120:121]
	v_and_b32_e32 v127, 0xffff0000, v123
	v_and_b32_e32 v126, 0xffff0000, v122
	v_pk_add_f32 v[150:151], v[114:115], v[116:117]
	v_lshlrev_b32_e32 v125, 16, v123
	v_lshlrev_b32_e32 v124, 16, v122
	v_pk_mul_f32 v[114:115], v[126:127], v[126:127]
	v_and_b32_e32 v123, 0xffff0000, v147
	v_pk_fma_f32 v[114:115], v[124:125], v[124:125], v[114:115]
	v_and_b32_e32 v122, 0xffff0000, v146
	v_pk_add_f32 v[152:153], v[114:115], v[114:115] op_sel:[0,1] op_sel_hi:[1,0]
	v_lshlrev_b32_e32 v121, 16, v147
	v_lshlrev_b32_e32 v120, 16, v146
	v_pk_mul_f32 v[114:115], v[122:123], v[122:123]
	v_lshlrev_b32_e32 v116, 16, v149
	v_pk_fma_f32 v[146:147], v[120:121], v[120:121], v[114:115]
	v_lshlrev_b32_e32 v114, 16, v148
	v_and_b32_e32 v115, 0xffff0000, v148
	v_and_b32_e32 v117, 0xffff0000, v149
	v_pk_add_f32 v[148:149], v[150:151], v[150:151] op_sel:[0,1] op_sel_hi:[1,0]
	v_mov_b32_e32 v150, v152
	v_mov_b32_e32 v106, v148
	v_mov_b32_e32 v151, v107
	v_mul_f32_e32 v0, v105, v105
	v_pk_add_f32 v[148:149], v[148:149], v[152:153]
	v_pk_mul_f32 v[150:151], v[106:107], v[150:151]
	v_pk_add_f32 v[146:147], v[146:147], v[146:147] op_sel:[0,1] op_sel_hi:[1,0]
	v_mov_b32_e32 v149, v151
	v_mov_b32_e32 v147, v0
	v_mul_f32_e32 v0, v115, v115
	v_pk_add_f32 v[146:147], v[148:149], v[146:147]
	v_pk_fma_f32 v[148:149], v[114:115], v[114:115], v[0:1] op_sel_hi:[1,1,0]
	v_mul_f32_e32 v0, v117, v117
	v_mul_f32_e32 v104, v108, v108
	v_mul_f32_e32 v110, v109, v109
	v_pk_fma_f32 v[150:151], v[116:117], v[116:117], v[0:1] op_sel_hi:[1,1,0]
	v_mov_b32_e32 v149, v104
	v_mov_b32_e32 v151, v110
	v_pk_add_f32 v[148:149], v[148:149], v[150:151]
	v_pk_add_f32 v[94:95], v[94:95], 1.0 op_sel_hi:[1,0]
	v_pk_add_f32 v[146:147], v[146:147], v[148:149]
	v_pk_add_f32 v[96:97], v[96:97], 1.0 op_sel_hi:[1,0]
	v_add_f32_e32 v0, v146, v147
	ds_bpermute_b32 v104, v140, v0
	v_lshl_add_u64 v[146:147], s[8:9], 0, v[100:101]
	v_pk_add_f32 v[88:89], v[88:89], 1.0 op_sel_hi:[1,0]
	v_pk_add_f32 v[86:87], v[86:87], 1.0 op_sel_hi:[1,0]
	s_waitcnt vmcnt(1)
	v_pk_add_f32 v[80:81], v[80:81], 1.0 op_sel_hi:[1,0]
	s_waitcnt lgkmcnt(0)
	v_add_f32_e32 v0, v0, v104
	ds_bpermute_b32 v104, v141, v0
	v_pk_add_f32 v[78:79], v[78:79], 1.0 op_sel_hi:[1,0]
	v_mov_b32_e32 v110, v113
	s_waitcnt vmcnt(0)
	v_pk_add_f32 v[72:73], v[72:73], 1.0 op_sel_hi:[1,0]
	v_pk_add_f32 v[70:71], v[70:71], 1.0 op_sel_hi:[1,0]
	s_waitcnt lgkmcnt(0)
	v_add_f32_e32 v0, v0, v104
	ds_bpermute_b32 v104, v142, v0
	v_pk_add_f32 v[64:65], v[64:65], 1.0 op_sel_hi:[1,0]
	v_pk_add_f32 v[62:63], v[62:63], 1.0 op_sel_hi:[1,0]
	v_pk_add_f32 v[56:57], v[56:57], 1.0 op_sel_hi:[1,0]
	v_pk_add_f32 v[54:55], v[54:55], 1.0 op_sel_hi:[1,0]
	s_waitcnt lgkmcnt(0)
	v_add_f32_e32 v0, v0, v104
	ds_bpermute_b32 v104, v143, v0
	v_pk_add_f32 v[48:49], v[48:49], 1.0 op_sel_hi:[1,0]
	v_pk_add_f32 v[46:47], v[46:47], 1.0 op_sel_hi:[1,0]
	v_readlane_b32 s6, v254, 13
	s_add_i32 s4, s4, s6
	s_waitcnt lgkmcnt(0)
	v_add_f32_e32 v0, v0, v104
	ds_bpermute_b32 v104, v144, v0
	v_pk_add_f32 v[40:41], v[40:41], 1.0 op_sel_hi:[1,0]
	v_pk_add_f32 v[38:39], v[38:39], 1.0 op_sel_hi:[1,0]
	s_add_u32 s8, s8, s86
	s_addc_u32 s9, s9, s87
	s_waitcnt lgkmcnt(0)
	v_add_f32_e32 v0, v0, v104
	ds_bpermute_b32 v104, v145, v0
	s_cmpk_lt_i32 s4, 0x2800
	v_readlane_b32 s7, v254, 14
	s_waitcnt lgkmcnt(0)
	v_add_f32_e32 v0, v0, v104
	v_fmamk_f32 v0, v0, 0x3a000000, v224
	v_rsq_f32_e32 v0, v0
	v_mov_b32_e32 v104, v107
	v_pk_mul_f32 v[136:137], v[0:1], v[136:137] op_sel_hi:[0,1]
	v_pk_mul_f32 v[138:139], v[0:1], v[138:139] op_sel_hi:[0,1]
	v_pk_mul_f32 v[136:137], v[10:11], v[136:137]
	v_pk_mul_f32 v[138:139], v[12:13], v[138:139]
	v_pk_fma_f32 v[90:91], v[94:95], v[136:137], v[90:91]
	v_pk_fma_f32 v[92:93], v[96:97], v[138:139], v[92:93]
	v_cvt_pk_bf16_f32 v94, v90, v91
	v_add_co_u32_e32 v90, vcc, s51, v146
	v_cvt_pk_bf16_f32 v95, v92, v93
	s_nop 0
	v_addc_co_u32_e32 v91, vcc, 0, v147, vcc
	v_mov_b32_e32 v92, v133
	v_mov_b32_e32 v93, v135
	v_mov_b32_e32 v133, v134
	global_store_dwordx2 v[90:91], v[94:95], off
	v_pk_mul_f32 v[92:93], v[0:1], v[92:93] op_sel_hi:[0,1]
	v_pk_mul_f32 v[94:95], v[0:1], v[132:133] op_sel_hi:[0,1]
	v_pk_mul_f32 v[94:95], v[2:3], v[94:95]
	v_pk_mul_f32 v[92:93], v[4:5], v[92:93]
	v_pk_fma_f32 v[82:83], v[86:87], v[94:95], v[82:83]
	v_pk_fma_f32 v[84:85], v[88:89], v[92:93], v[84:85]
	v_cvt_pk_bf16_f32 v82, v82, v83
	v_cvt_pk_bf16_f32 v83, v84, v85
	global_store_dwordx2 v[90:91], v[82:83], off offset:512
	v_pk_mul_f32 v[82:83], v[0:1], v[130:131] op_sel_hi:[0,1]
	v_pk_mul_f32 v[84:85], v[0:1], v[128:129] op_sel_hi:[0,1]
	v_pk_mul_f32 v[84:85], v[6:7], v[84:85]
	v_pk_mul_f32 v[82:83], v[8:9], v[82:83]
	v_pk_fma_f32 v[74:75], v[78:79], v[84:85], v[74:75]
	v_pk_fma_f32 v[76:77], v[80:81], v[82:83], v[76:77]
	v_cvt_pk_bf16_f32 v74, v74, v75
	v_cvt_pk_bf16_f32 v75, v76, v77
	global_store_dwordx2 v[90:91], v[74:75], off offset:1024
	v_pk_mul_f32 v[74:75], v[118:119], v[0:1] op_sel_hi:[1,0]
	v_pk_mul_f32 v[76:77], v[110:111], v[0:1] op_sel_hi:[1,0]
	v_pk_mul_f32 v[74:75], v[16:17], v[74:75]
	v_pk_mul_f32 v[76:77], v[14:15], v[76:77]
	v_pk_fma_f32 v[68:69], v[72:73], v[74:75], v[68:69]
	v_pk_fma_f32 v[66:67], v[70:71], v[76:77], v[66:67]
	s_nop 0
	v_cvt_pk_bf16_f32 v66, v66, v67
	v_cvt_pk_bf16_f32 v67, v68, v69
	global_store_dwordx2 v[90:91], v[66:67], off offset:1536
	v_mov_b32_e32 v66, v125
	v_mov_b32_e32 v67, v127
	v_mov_b32_e32 v125, v126
	v_pk_mul_f32 v[66:67], v[0:1], v[66:67] op_sel_hi:[0,1]
	v_pk_mul_f32 v[68:69], v[0:1], v[124:125] op_sel_hi:[0,1]
	v_pk_mul_f32 v[68:69], v[18:19], v[68:69]
	v_pk_mul_f32 v[66:67], v[20:21], v[66:67]
	v_pk_fma_f32 v[58:59], v[62:63], v[68:69], v[58:59]
	v_pk_fma_f32 v[60:61], v[64:65], v[66:67], v[60:61]
	v_cvt_pk_bf16_f32 v58, v58, v59
	v_cvt_pk_bf16_f32 v59, v60, v61
	global_store_dwordx2 v[90:91], v[58:59], off offset:2048
	v_mov_b32_e32 v58, v121
	v_mov_b32_e32 v59, v123
	v_mov_b32_e32 v121, v122
	v_pk_mul_f32 v[58:59], v[0:1], v[58:59] op_sel_hi:[0,1]
	v_pk_mul_f32 v[60:61], v[0:1], v[120:121] op_sel_hi:[0,1]
	v_pk_mul_f32 v[60:61], v[22:23], v[60:61]
	v_pk_mul_f32 v[58:59], v[24:25], v[58:59]
	v_pk_fma_f32 v[50:51], v[54:55], v[60:61], v[50:51]
	v_pk_fma_f32 v[52:53], v[56:57], v[58:59], v[52:53]
	v_cvt_pk_bf16_f32 v50, v50, v51
	v_cvt_pk_bf16_f32 v51, v52, v53
	global_store_dwordx2 v[90:91], v[50:51], off offset:2560
	v_pk_mul_f32 v[50:51], v[0:1], v[116:117] op_sel_hi:[0,1]
	v_pk_mul_f32 v[52:53], v[0:1], v[114:115] op_sel_hi:[0,1]
	v_pk_mul_f32 v[52:53], v[26:27], v[52:53]
	v_pk_mul_f32 v[50:51], v[28:29], v[50:51]
	v_pk_fma_f32 v[42:43], v[46:47], v[52:53], v[42:43]
	v_pk_fma_f32 v[44:45], v[48:49], v[50:51], v[44:45]
	v_cvt_pk_bf16_f32 v42, v42, v43
	v_cvt_pk_bf16_f32 v43, v44, v45
	global_store_dwordx2 v[90:91], v[42:43], off offset:3072
	v_pk_mul_f32 v[42:43], v[108:109], v[0:1] op_sel_hi:[1,0]
	v_pk_mul_f32 v[44:45], v[104:105], v[0:1] op_sel_hi:[1,0]
	v_pk_mul_f32 v[42:43], v[32:33], v[42:43]
	v_pk_mul_f32 v[44:45], v[30:31], v[44:45]
	v_pk_fma_f32 v[36:37], v[40:41], v[42:43], v[36:37]
	v_pk_fma_f32 v[34:35], v[38:39], v[44:45], v[34:35]
	s_nop 0
	v_cvt_pk_bf16_f32 v34, v34, v35
	v_cvt_pk_bf16_f32 v35, v36, v37
	global_store_dwordx2 v[90:91], v[34:35], off offset:3584
	s_cbranch_scc1 .LBB0_1600
